# scan: output waves wait vmcnt(16) instead of 0 before the staging writes (their 16 result stores stay in flight), on top of v31
# baseline (speedup 1.0000x reference)
; __device__ __forceinline__ int mk_tid() { int t = (int)threadIdx.x; asm volatile("" : "+v"(t)); return t; }
; __device__ __forceinline__ unsigned short f2bf(float f) { unsigned u = __float_as_uint(f); return (unsigned short)((u + 0x7fffu + ((u >> 16) & 1u)) >> 16); }
; __device__ __forceinline__ unsigned f2bf(float f) { return pk2(f, 0.f) & 0xffffu; }
; __device__ __forceinline__ void gla_scan_phase(const Ctx& c, LAS unsigned char* lds) {
;     ...
;             if (st + 1 < NCH) SC_STORE(mk_tid());
;             if (st + 2 < NCH) SC_LOAD(chn2, mk_tid());
;             if (wid < 4) {
;                 const int ib = wid & 1, eb = wid >> 1;
;                 const int col = h * 512 + es * 64 + 32 * eb + r32;
;                 const int rbase = (ch == 0 ? NREAL + b * NMETA - 48 : b * SEQ + (ch - 1) * 64) + 32 * ib + 4 * hi;
;                 bf16_t* obase = dir == 0 ? Pw : A; const int ostride = dir == 0 ? GLA_NP : DM;
;                 bf16_t* dst0 = obase + (size_t)rbase * ostride + col;
; #pragma unroll
;                 for (int r = 0; r < 16; ++r) { const int io = (r & 3) + 8 * (r >> 2);
;                     if (ch > 0 || 32 * ib + 4 * hi + io >= 48) dst0[(size_t)io * ostride] = (bf16_t)f2bf(acc[r]); }
.LBB0_766:
	s_cmp_eq_u32 s60, 64
	s_cbranch_scc1 .LBB0_770
	s_mov_b64 vcc, s[20:21]
	s_cbranch_vccnz .Lscan_w0_a
	s_cmp_lt_u32 s60, 2
	s_cbranch_scc1 .Lscan_w0_a
	s_waitcnt vmcnt(16)
	s_branch .Lscan_w1_a

.Lscan_w1_a:
	ds_write_b128 v156, v[152:155]
	ds_write_b128 v156, v[160:163] offset:8448
	ds_write_b128 v156, v[168:171] offset:16896
	ds_write_b128 v156, v[176:179] offset:25344
	ds_write_b128 v157, v[184:187]
	ds_write_b16 v158, v188
	ds_write_b16_d16_hi v158, v188 offset:144
	ds_write_b16 v158, v189 offset:288
	ds_write_b16_d16_hi v158, v189 offset:432
	ds_write_b16 v158, v190 offset:576
	ds_write_b16_d16_hi v158, v190 offset:720
	ds_write_b16 v158, v191 offset:864
	ds_write_b16_d16_hi v158, v191 offset:1008
	v_cmp_gt_i32_e32 vcc, 64, v200
	s_and_saveexec_b64 s[0:1], vcc
	ds_write_b128 v159, v[148:151]
	s_or_b64 exec, exec, s[0:1]

; __device__ __forceinline__ void gla_onorm_phase(const Ctx& c, int j) {
;     const bf16_t* P = (const bf16_t*)(c.ws + WS_P); bf16_t* A = (bf16_t*)(c.ws + WS_A);
;     const float* nw = c.gla_o_norm + j * 512;
;     const int gw = blockIdx.x * 8 + c.wave, NGW = c.G * 8;
;     float w8[8];
; #pragma unroll
;     for (int e = 0; e < 8; ++e) w8[e] = nw[c.lane * 8 + e];
;     for (int row = gw; row < MV; row += NGW) {
; #pragma unroll
;         for (int hh = 0; hh < 4; ++hh) {
;             const int col = hh * 512 + c.lane * 8;
;             const u32x4 a = *(const u32x4*)(P + (size_t)row * GLA_NP + col), bq = *(const u32x4*)(A + (size_t)row * DM + col), gq = *(const u32x4*)(P + (size_t)row * GLA_NP + 4096 + col);
;             const unsigned aw[4] = {a.x, a.y, a.z, a.w}, bw[4] = {bq.x, bq.y, bq.z, bq.w}, gw4[4] = {gq.x, gq.y, gq.z, gq.w};
;             float o[8], g[8]; float ss = 0.f;
; #pragma unroll
;             for (int e = 0; e < 4; ++e) {
;                 o[2 * e] = __uint_as_float(aw[e] << 16) + __uint_as_float(bw[e] << 16); o[2 * e + 1] = __uint_as_float(aw[e] & 0xffff0000u) + __uint_as_float(bw[e] & 0xffff0000u);
;                 g[2 * e] = __uint_as_float(gw4[e] << 16); g[2 * e + 1] = __uint_as_float(gw4[e] & 0xffff0000u);
;                 ss += o[2 * e] * o[2 * e] + o[2 * e + 1] * o[2 * e + 1]; }
;             const float rstd = 1.0f / sqrtf(wave_sum(ss) * (1.f / 512.f) + NORM_EPS);
.LBB0_853:
	s_or_b64 exec, exec, s[2:3]
	s_waitcnt lgkmcnt(0)
	s_barrier
	s_nop 0
	s_nop 0
	s_nop 0
	s_nop 0
	s_nop 0
	s_nop 0
	s_nop 0
	s_nop 0
	s_nop 0
	s_nop 0
	s_nop 0
.LBB0_854:
	s_cmp_lt_i32 s74, 13
	s_cselect_b64 s[0:1], -1, 0
	s_cmp_gt_i32 s75, 12
	s_cselect_b64 s[2:3], -1, 0
	s_and_b64 s[0:1], s[0:1], s[2:3]
	s_andn2_b64 vcc, exec, s[0:1]
	s_cbranch_vccnz .LBB0_912
	v_mov_b32_e32 v8, v200
	s_lshl_b32 s1, s76, 3
	v_readfirstlane_b32 s0, v8
	s_ashr_i32 s0, s0, 6
	s_add_i32 s20, s0, s1
	s_cmpk_gt_i32 s20, 0x403f
	s_cbranch_scc1 .LBB0_858
	v_lshlrev_b32_e32 v0, 5, v8
	v_readlane_b32 s0, v254, 0
	v_and_b32_e32 v9, 0x7e0, v0
	v_readlane_b32 s6, v254, 6
	v_readlane_b32 s7, v254, 7
	s_nop 4
	global_load_dwordx4 v[0:3], v9, s[6:7]
	global_load_dwordx4 v[4:7], v9, s[6:7] offset:16
	v_mbcnt_lo_u32_b32 v9, -1, 0
	v_mbcnt_hi_u32_b32 v9, -1, v9
	v_and_b32_e32 v10, 64, v9
	v_add_u32_e32 v10, 64, v10
	v_xor_b32_e32 v11, 1, v9
	v_cmp_lt_i32_e32 vcc, v11, v10
	v_readlane_b32 s1, v254, 1
	s_ashr_i32 s21, s20, 31
	v_cndmask_b32_e32 v11, v9, v11, vcc
	v_lshlrev_b32_e32 v16, 2, v11
	v_xor_b32_e32 v11, 2, v9
	v_cmp_lt_i32_e32 vcc, v11, v10
	s_lshl_b32 s22, s63, 3
	s_lshl_b64 s[0:1], s[20:21], 12
	v_cndmask_b32_e32 v11, v9, v11, vcc
	v_lshlrev_b32_e32 v17, 2, v11
	v_xor_b32_e32 v11, 4, v9
	v_cmp_lt_i32_e32 vcc, v11, v10
	s_add_u32 s24, s72, s0
	s_addc_u32 s25, s73, s1
	v_cndmask_b32_e32 v11, v9, v11, vcc
	s_waitcnt vmcnt(0)
	v_lshlrev_b32_e32 v18, 2, v11
	v_xor_b32_e32 v11, 8, v9
	v_cmp_lt_i32_e32 vcc, v11, v10
	s_ashr_i32 s23, s22, 31
	s_lshl_b64 s[26:27], s[22:23], 12
	v_cndmask_b32_e32 v11, v9, v11, vcc
	v_lshlrev_b32_e32 v19, 2, v11
	v_xor_b32_e32 v11, 16, v9
	v_cmp_lt_i32_e32 vcc, v11, v10
	s_mul_i32 s1, s20, 0x3040
	v_and_b32_e32 v8, 63, v8
	v_cndmask_b32_e32 v11, v9, v11, vcc
	v_lshlrev_b32_e32 v20, 2, v11
	v_xor_b32_e32 v11, 32, v9
	v_cmp_lt_i32_e32 vcc, v11, v10
	s_mul_hi_i32 s0, s20, 0x3040
	s_add_u32 s28, s72, s1
	v_cndmask_b32_e32 v9, v9, v11, vcc
	v_lshlrev_b32_e32 v21, 2, v9
	v_lshlrev_b32_e32 v8, 4, v8
	v_mov_b32_e32 v9, 0
	s_addc_u32 s29, s73, s0
	s_mul_i32 s0, s63, 0x18200
	s_mul_hi_i32 s1, s22, 0x3040
	v_mov_b32_e32 v22, 0x358637bd
	s_mov_b32 s21, 0xf800000
	v_mov_b32_e32 v23, 0x260
	v_readlane_b32 s2, v254, 2
	v_readlane_b32 s3, v254, 3
	v_readlane_b32 s4, v254, 4
	v_readlane_b32 s5, v254, 5

; __device__ __forceinline__ int mk_tid() { int t = (int)threadIdx.x; asm volatile("" : "+v"(t)); return t; }
; __device__ __forceinline__ unsigned short f2bf(float f) { unsigned u = __float_as_uint(f); return (unsigned short)((u + 0x7fffu + ((u >> 16) & 1u)) >> 16); }
; __device__ __forceinline__ unsigned f2bf(float f) { return pk2(f, 0.f) & 0xffffu; }
; __device__ __forceinline__ void gla_scan_phase(const Ctx& c, LAS unsigned char* lds) {
;     ...
;             if (st + 1 < NCH) SC_STORE(mk_tid());
;             if (st + 2 < NCH) SC_LOAD(chn2, mk_tid());
;             if (wid < 4) {
;                 const int ib = wid & 1, eb = wid >> 1;
;                 const int col = h * 512 + es * 64 + 32 * eb + r32;
;                 const int rbase = (ch == 0 ? NREAL + b * NMETA - 48 : b * SEQ + (ch - 1) * 64) + 32 * ib + 4 * hi;
;                 bf16_t* obase = dir == 0 ? Pw : A; const int ostride = dir == 0 ? GLA_NP : DM;
;                 bf16_t* dst0 = obase + (size_t)rbase * ostride + col;
; #pragma unroll
;                 for (int r = 0; r < 16; ++r) { const int io = (r & 3) + 8 * (r >> 2);
;                     if (ch > 0 || 32 * ib + 4 * hi + io >= 48) dst0[(size_t)io * ostride] = (bf16_t)f2bf(acc[r]); }
.LBB0_1722:
	s_cmp_eq_u32 s92, 64
	s_cbranch_scc1 .LBB0_1726
	s_mov_b64 vcc, s[20:21]
	s_cbranch_vccnz .Lscan_w0_b
	s_cmp_lt_u32 s92, 2
	s_cbranch_scc1 .Lscan_w0_b
	s_waitcnt vmcnt(16)
	s_branch .Lscan_w1_b

; __device__ __forceinline__ void gla_onorm_phase(const Ctx& c, int j) {
;     const bf16_t* P = (const bf16_t*)(c.ws + WS_P); bf16_t* A = (bf16_t*)(c.ws + WS_A);
;     const float* nw = c.gla_o_norm + j * 512;
;     const int gw = blockIdx.x * 8 + c.wave, NGW = c.G * 8;
;     float w8[8];
; #pragma unroll
;     for (int e = 0; e < 8; ++e) w8[e] = nw[c.lane * 8 + e];
;     for (int row = gw; row < MV; row += NGW) {
; #pragma unroll
;         for (int hh = 0; hh < 4; ++hh) {
;             const int col = hh * 512 + c.lane * 8;
;             const u32x4 a = *(const u32x4*)(P + (size_t)row * GLA_NP + col), bq = *(const u32x4*)(A + (size_t)row * DM + col), gq = *(const u32x4*)(P + (size_t)row * GLA_NP + 4096 + col);
;             const unsigned aw[4] = {a.x, a.y, a.z, a.w}, bw[4] = {bq.x, bq.y, bq.z, bq.w}, gw4[4] = {gq.x, gq.y, gq.z, gq.w};
;             float o[8], g[8]; float ss = 0.f;
; #pragma unroll
;             for (int e = 0; e < 4; ++e) {
;                 o[2 * e] = __uint_as_float(aw[e] << 16) + __uint_as_float(bw[e] << 16); o[2 * e + 1] = __uint_as_float(aw[e] & 0xffff0000u) + __uint_as_float(bw[e] & 0xffff0000u);
;                 g[2 * e] = __uint_as_float(gw4[e] << 16); g[2 * e + 1] = __uint_as_float(gw4[e] & 0xffff0000u);
;                 ss += o[2 * e] * o[2 * e] + o[2 * e + 1] * o[2 * e + 1]; }
;             const float rstd = 1.0f / sqrtf(wave_sum(ss) * (1.f / 512.f) + NORM_EPS);
.LBB0_1809:
	s_or_b64 exec, exec, s[2:3]
	s_waitcnt lgkmcnt(0)
	s_barrier
	s_nop 0
	s_nop 0
	s_nop 0
	s_nop 0
	s_nop 0
	s_nop 0
	s_nop 0
	s_nop 0
	s_nop 0
.LBB0_1810:
	s_cmp_lt_i32 s74, 29
	s_cselect_b64 s[0:1], -1, 0
	s_cmp_gt_i32 s75, 28
	s_cselect_b64 s[2:3], -1, 0
	s_and_b64 s[0:1], s[0:1], s[2:3]
	s_andn2_b64 vcc, exec, s[0:1]
	s_cbranch_vccnz .LBB0_1868
	v_mov_b32_e32 v8, v200
	s_lshl_b32 s1, s76, 3
	v_readfirstlane_b32 s0, v8
	s_ashr_i32 s0, s0, 6
	s_add_i32 s20, s0, s1
	s_cmpk_gt_i32 s20, 0x403f
	s_cbranch_scc1 .LBB0_1814
	v_lshlrev_b32_e32 v0, 5, v8
	v_readlane_b32 s0, v254, 0
	v_and_b32_e32 v9, 0x7e0, v0
	v_readlane_b32 s6, v254, 6
	v_readlane_b32 s7, v254, 7
	s_nop 4
	global_load_dwordx4 v[0:3], v9, s[6:7] offset:2048
	global_load_dwordx4 v[4:7], v9, s[6:7] offset:2064
	v_mbcnt_lo_u32_b32 v9, -1, 0
	v_mbcnt_hi_u32_b32 v9, -1, v9
	v_and_b32_e32 v10, 64, v9
	v_add_u32_e32 v10, 64, v10
	v_xor_b32_e32 v11, 1, v9
	v_cmp_lt_i32_e32 vcc, v11, v10
	v_readlane_b32 s1, v254, 1
	s_ashr_i32 s21, s20, 31
	v_cndmask_b32_e32 v11, v9, v11, vcc
	v_lshlrev_b32_e32 v16, 2, v11
	v_xor_b32_e32 v11, 2, v9
	v_cmp_lt_i32_e32 vcc, v11, v10
	s_lshl_b32 s22, s63, 3
	s_lshl_b64 s[0:1], s[20:21], 12
	v_cndmask_b32_e32 v11, v9, v11, vcc
	v_lshlrev_b32_e32 v17, 2, v11
	v_xor_b32_e32 v11, 4, v9
	v_cmp_lt_i32_e32 vcc, v11, v10
	s_add_u32 s24, s72, s0
	s_addc_u32 s25, s73, s1
	v_cndmask_b32_e32 v11, v9, v11, vcc
	s_waitcnt vmcnt(0)
	v_lshlrev_b32_e32 v18, 2, v11
	v_xor_b32_e32 v11, 8, v9
	v_cmp_lt_i32_e32 vcc, v11, v10
	s_ashr_i32 s23, s22, 31
	s_lshl_b64 s[26:27], s[22:23], 12
	v_cndmask_b32_e32 v11, v9, v11, vcc
	v_lshlrev_b32_e32 v19, 2, v11
	v_xor_b32_e32 v11, 16, v9
	v_cmp_lt_i32_e32 vcc, v11, v10
	s_mul_i32 s1, s20, 0x3040
	v_and_b32_e32 v8, 63, v8
	v_cndmask_b32_e32 v11, v9, v11, vcc
	v_lshlrev_b32_e32 v20, 2, v11
	v_xor_b32_e32 v11, 32, v9
	v_cmp_lt_i32_e32 vcc, v11, v10
	s_mul_hi_i32 s0, s20, 0x3040
	s_add_u32 s28, s72, s1
	v_cndmask_b32_e32 v9, v9, v11, vcc
	v_lshlrev_b32_e32 v21, 2, v9
	v_lshlrev_b32_e32 v8, 4, v8
	v_mov_b32_e32 v9, 0
	s_addc_u32 s29, s73, s0
	s_mul_i32 s0, s63, 0x18200
	s_mul_hi_i32 s1, s22, 0x3040
	v_mov_b32_e32 v22, 0x358637bd
	s_mov_b32 s21, 0xf800000
	v_mov_b32_e32 v23, 0x260
	v_readlane_b32 s2, v254, 2
	v_readlane_b32 s3, v254, 3
	v_readlane_b32 s4, v254, 4
	v_readlane_b32 s5, v254, 5
